# s_setprio 1 around the PV MFMA phase of prompt attention
# speedup vs baseline: 1.0801x; 1.0052x over previous
.LBB0_1014:
	s_min_u32 s5, s4, s3
	s_lshl_b32 s8, s5, 7
	v_lshl_add_u64 v[116:117], v[174:175], 0, s[8:9]
	s_mul_i32 s8, s5, 0x30000
	v_lshl_add_u64 v[112:113], v[172:173], 0, s[8:9]
	global_load_dwordx4 v[84:87], v[112:113], off offset:1024
	global_load_dwordx4 v[88:91], v[116:117], off
	ds_read_b128 v[152:155], v237 offset:35840
	ds_read_b128 v[156:159], v237 offset:35904
	v_add_co_u32_e32 v92, vcc, 0xc000, v112
	s_mov_b32 s7, s9
	s_nop 0
	v_addc_co_u32_e32 v93, vcc, 0, v113, vcc
	s_waitcnt lgkmcnt(1)
	v_mfma_f32_16x16x32_bf16 v[152:155], v[152:155], v[60:63], v[108:111]
	v_add_co_u32_e32 v96, vcc, 0x100000, v116
	ds_read_b128 v[160:163], v237 offset:40256
	s_waitcnt lgkmcnt(1)
	v_mfma_f32_16x16x32_bf16 v[152:155], v[156:159], v[64:67], v[152:155]
	ds_read_b128 v[156:159], v237 offset:40192
	v_addc_co_u32_e32 v97, vcc, 0, v117, vcc
	v_add_co_u32_e32 v100, vcc, 0x18000, v112
	global_load_dwordx4 v[92:95], v[92:93], off offset:1024
	s_waitcnt lgkmcnt(0)
	v_mfma_f32_16x16x32_bf16 v[156:159], v[156:159], v[60:63], v[108:111]
	ds_read_b128 v[164:167], v237 offset:44608
	s_nop 0
	v_exp_f32_e32 v199, v155
	v_exp_f32_e32 v191, v153
	v_mfma_f32_16x16x32_bf16 v[156:159], v[160:163], v[64:67], v[156:159]
	ds_read_b128 v[160:163], v237 offset:44544
	v_addc_co_u32_e32 v101, vcc, 0, v113, vcc
	s_waitcnt lgkmcnt(0)
	v_mfma_f32_16x16x32_bf16 v[160:163], v[160:163], v[60:63], v[108:111]
	s_nop 1
	s_nop 1
	v_exp_f32_e32 v197, v157
	v_exp_f32_e32 v189, v156
	v_exp_f32_e32 v195, v158
	v_mfma_f32_16x16x32_bf16 v[180:183], v[164:167], v[64:67], v[160:163]
	ds_read_b128 v[164:167], v237 offset:48960
	v_exp_f32_e32 v201, v159
	ds_read_b128 v[160:163], v237 offset:48896
	s_waitcnt lgkmcnt(0)
	v_mfma_f32_16x16x32_bf16 v[160:163], v[160:163], v[60:63], v[108:111]
	s_nop 1
	s_nop 0
	v_exp_f32_e32 v185, v183
	ds_read_b128 v[220:223], v237 offset:36032
	v_exp_f32_e32 v181, v181
	v_mfma_f32_16x16x32_bf16 v[210:213], v[164:167], v[64:67], v[160:163]
	v_exp_f32_e32 v167, v154
	v_exp_f32_e32 v165, v152
	s_nop 0
	v_exp_f32_e32 v161, v180
	s_nop 2
	s_nop 0
	v_exp_f32_e32 v179, v210
	v_exp_f32_e32 v187, v211
	v_exp_f32_e32 v183, v212
	v_exp_f32_e32 v193, v213
	ds_read_b128 v[210:213], v237 offset:35968
	s_waitcnt lgkmcnt(0)
	v_mfma_f32_16x16x32_bf16 v[210:213], v[210:213], v[68:71], v[108:111]
	ds_read_b128 v[224:227], v237 offset:40384
	ds_read_b128 v[240:243], v237 offset:44736
	v_mfma_f32_16x16x32_bf16 v[210:213], v[220:223], v[72:75], v[210:213]
	ds_read_b128 v[220:223], v237 offset:40320
	v_exp_f32_e32 v163, v182
	s_waitcnt lgkmcnt(0)
	v_mfma_f32_16x16x32_bf16 v[220:223], v[220:223], v[68:71], v[108:111]
	v_mfma_f32_16x16x32_bf16 v[220:223], v[224:227], v[72:75], v[220:223]
	ds_read_b128 v[224:227], v237 offset:44672
	v_cvt_pk_bf16_f32 v157, v167, v199
	s_waitcnt lgkmcnt(0)
	v_mfma_f32_16x16x32_bf16 v[224:227], v[224:227], v[68:71], v[108:111]
	v_mfma_f32_16x16x32_bf16 v[224:227], v[240:243], v[72:75], v[224:227]
	ds_read_b128 v[240:243], v237 offset:49024
	ds_read_b128 v[244:247], v237 offset:49088
	v_cvt_pk_bf16_f32 v156, v165, v191
	v_exp_f32_e32 v164, v210
	v_exp_f32_e32 v190, v211
	v_exp_f32_e32 v166, v212
	v_exp_f32_e32 v198, v213
	s_waitcnt lgkmcnt(1)
	v_mfma_f32_16x16x32_bf16 v[240:243], v[240:243], v[68:71], v[108:111]
	v_exp_f32_e32 v188, v220
	v_pk_add_f32 v[210:211], v[164:165], 0 op_sel_hi:[1,0]
	v_exp_f32_e32 v196, v221
	v_pk_add_f32 v[210:211], v[190:191], v[210:211]
	v_cvt_pk_bf16_f32 v159, v195, v201
	v_pk_add_f32 v[210:211], v[166:167], v[210:211]
	v_exp_f32_e32 v194, v222
	v_cvt_pk_bf16_f32 v158, v189, v197
	v_pk_add_f32 v[210:211], v[198:199], v[210:211]
	v_exp_f32_e32 v200, v223
	v_cvt_pk_bf16_f32 v155, v183, v193
	v_cvt_pk_bf16_f32 v152, v161, v181
	s_waitcnt lgkmcnt(0)
	v_mfma_f32_16x16x32_bf16 v[240:243], v[244:247], v[72:75], v[240:243]
	v_add_f32_e64 v210, v210, v188
	v_add_f32_e64 v211, v211, v189
	v_exp_f32_e32 v160, v224
	v_cvt_pk_bf16_f32 v154, v179, v187
	v_cvt_pk_bf16_f32 v153, v163, v185
	v_pk_add_f32 v[210:211], v[196:197], v[210:211]
	v_exp_f32_e32 v180, v225
	v_exp_f32_e32 v162, v226
	v_pk_add_f32 v[210:211], v[194:195], v[210:211]
	v_exp_f32_e32 v184, v227
	v_pk_add_f32 v[210:211], v[200:201], v[210:211]
	v_exp_f32_e32 v178, v240
	v_pk_add_f32 v[210:211], v[210:211], v[160:161]
	v_exp_f32_e32 v186, v241
	v_pk_add_f32 v[210:211], v[180:181], v[210:211]
	v_exp_f32_e32 v182, v242
	v_pk_add_f32 v[210:211], v[162:163], v[210:211]
	v_pk_add_f32 v[210:211], v[184:185], v[210:211]
	v_pk_add_f32 v[210:211], v[210:211], v[178:179]
	v_bfe_u32 v165, v166, 16, 1
	v_exp_f32_e32 v192, v243
	v_pk_add_f32 v[210:211], v[186:187], v[210:211]
	v_bfe_u32 v163, v198, 16, 1
	v_add3_u32 v165, v166, v165, s33
	v_pk_add_f32 v[210:211], v[182:183], v[210:211]
	v_add3_u32 v163, v198, v163, s33
	v_lshrrev_b32_e32 v165, 16, v165
	v_and_or_b32 v165, v163, s6, v165
	v_cvt_pk_bf16_f32 v166, v188, v196
	v_bfe_u32 v163, v184, 16, 1
	v_add3_u32 v183, v184, v163, s33
	v_bfe_u32 v163, v162, 16, 1
	v_bfe_u32 v181, v182, 16, 1
	v_bfe_u32 v185, v178, 16, 1
	v_cvt_pk_bf16_f32 v167, v194, v200
	v_cvt_pk_bf16_f32 v164, v164, v190
	v_bfe_u32 v161, v192, 16, 1
	v_bfe_u32 v179, v186, 16, 1
	v_add3_u32 v181, v182, v181, s33
	v_add3_u32 v162, v162, v163, s33
	v_add3_u32 v163, v178, v185, s33
	v_add3_u32 v161, v192, v161, s33
	v_add3_u32 v179, v186, v179, s33
	v_lshrrev_b32_e32 v162, 16, v162
	v_lshrrev_b32_e32 v178, 16, v181
	v_lshrrev_b32_e32 v181, 16, v163
	v_add_u32_e32 v182, 0xd000, v238
	v_and_or_b32 v163, v161, s6, v178
	v_and_or_b32 v161, v183, s6, v162
	v_and_or_b32 v162, v179, s6, v181
	v_cvt_pk_bf16_f32 v160, v160, v180
	s_setprio 1
	ds_read2_b64 v[178:181], v182 offset1:4
	ds_read2_b64 v[216:219], v182 offset0:8 offset1:12
	s_waitcnt lgkmcnt(1)
	v_mfma_f32_16x16x32_bf16 v[76:79], v[178:181], v[156:159], v[76:79]
	v_add_co_u32_e32 v104, vcc, 0x200000, v116
	global_load_dwordx4 v[96:99], v[96:97], off
	v_mfma_f32_16x16x32_bf16 v[80:83], v[178:181], v[164:167], v[80:83]
	v_add_u32_e32 v182, 0xd800, v238
	v_addc_co_u32_e32 v105, vcc, 0, v117, vcc
	ds_read2_b64 v[178:181], v182 offset0:32 offset1:36
	s_waitcnt lgkmcnt(1)
	v_mfma_f32_16x16x32_bf16 v[76:79], v[216:219], v[152:155], v[76:79]
	v_add_co_u32_e32 v112, vcc, 0x24000, v112
	global_load_dwordx4 v[100:103], v[100:101], off offset:1024
	v_mfma_f32_16x16x32_bf16 v[80:83], v[216:219], v[160:163], v[80:83]
	v_addc_co_u32_e32 v113, vcc, 0, v113, vcc
	ds_read2_b64 v[216:219], v182 offset0:40 offset1:44
	s_waitcnt lgkmcnt(1)
	v_mfma_f32_16x16x32_bf16 v[24:27], v[178:181], v[156:159], v[24:27]
	v_add_co_u32_e32 v116, vcc, 0x300000, v116
	global_load_dwordx4 v[104:107], v[104:105], off
	v_mfma_f32_16x16x32_bf16 v[36:39], v[178:181], v[164:167], v[36:39]
	v_add_u32_e32 v182, 0xe000, v238
	v_addc_co_u32_e32 v117, vcc, 0, v117, vcc
	ds_read2_b64 v[178:181], v182 offset0:64 offset1:68
	s_waitcnt lgkmcnt(1)
	v_mfma_f32_16x16x32_bf16 v[24:27], v[216:219], v[152:155], v[24:27]
	global_load_dwordx4 v[112:115], v[112:113], off offset:1024
	v_pk_add_f32 v[210:211], v[192:193], v[210:211]
	global_load_dwordx4 v[116:119], v[116:117], off
	v_mfma_f32_16x16x32_bf16 v[36:39], v[216:219], v[160:163], v[36:39]
	v_pk_add_f32 v[176:177], v[176:177], v[210:211]
	ds_read2_b64 v[216:219], v182 offset0:72 offset1:76
	s_waitcnt lgkmcnt(1)
	v_mfma_f32_16x16x32_bf16 v[16:19], v[178:181], v[156:159], v[16:19]
	v_mfma_f32_16x16x32_bf16 v[32:35], v[178:181], v[164:167], v[32:35]
	v_add_u32_e32 v182, 0xe800, v238
	ds_read2_b64 v[178:181], v182 offset0:96 offset1:100
	s_waitcnt lgkmcnt(1)
	v_mfma_f32_16x16x32_bf16 v[16:19], v[216:219], v[152:155], v[16:19]
	v_mfma_f32_16x16x32_bf16 v[32:35], v[216:219], v[160:163], v[32:35]
	ds_read2_b64 v[216:219], v182 offset0:104 offset1:108
	s_waitcnt lgkmcnt(1)
	v_mfma_f32_16x16x32_bf16 v[28:31], v[178:181], v[156:159], v[28:31]
	v_mfma_f32_16x16x32_bf16 v[44:47], v[178:181], v[164:167], v[44:47]
	v_add_u32_e32 v182, 0xf000, v238
	ds_read2_b64 v[178:181], v182 offset0:128 offset1:132
	s_waitcnt lgkmcnt(1)
	v_mfma_f32_16x16x32_bf16 v[28:31], v[216:219], v[152:155], v[28:31]
	v_mfma_f32_16x16x32_bf16 v[44:47], v[216:219], v[160:163], v[44:47]
	ds_read2_b64 v[216:219], v182 offset0:136 offset1:140
	s_waitcnt lgkmcnt(1)
	v_mfma_f32_16x16x32_bf16 v[40:43], v[178:181], v[156:159], v[40:43]
	v_mfma_f32_16x16x32_bf16 v[52:55], v[178:181], v[164:167], v[52:55]
	v_add_u32_e32 v182, 0xf800, v238
	ds_read2_b64 v[178:181], v182 offset0:160 offset1:164
	s_waitcnt lgkmcnt(1)
	v_mfma_f32_16x16x32_bf16 v[40:43], v[216:219], v[152:155], v[40:43]
	v_mfma_f32_16x16x32_bf16 v[52:55], v[216:219], v[160:163], v[52:55]
	ds_read2_b64 v[216:219], v182 offset0:168 offset1:172
	s_waitcnt lgkmcnt(1)
	v_mfma_f32_16x16x32_bf16 v[12:15], v[178:181], v[156:159], v[12:15]
	v_mfma_f32_16x16x32_bf16 v[48:51], v[178:181], v[164:167], v[48:51]
	v_add_u32_e32 v182, 0xd000, v235
	ds_read2_b64 v[178:181], v182 offset1:4
	s_waitcnt lgkmcnt(1)
	v_mfma_f32_16x16x32_bf16 v[12:15], v[216:219], v[152:155], v[12:15]
	v_mfma_f32_16x16x32_bf16 v[48:51], v[216:219], v[160:163], v[48:51]
	ds_read2_b64 v[216:219], v182 offset0:8 offset1:12
	s_waitcnt lgkmcnt(1)
	v_mfma_f32_16x16x32_bf16 v[4:7], v[178:181], v[156:159], v[4:7]
	v_mfma_f32_16x16x32_bf16 v[8:11], v[178:181], v[164:167], v[8:11]
	v_add_u32_e32 v182, 0xd000, v236
	ds_read2_b64 v[178:181], v182 offset1:4
	s_waitcnt lgkmcnt(1)
	v_mfma_f32_16x16x32_bf16 v[4:7], v[216:219], v[152:155], v[4:7]
	v_mfma_f32_16x16x32_bf16 v[8:11], v[216:219], v[160:163], v[8:11]
	s_waitcnt lgkmcnt(0)
	v_mfma_f32_16x16x32_bf16 v[20:23], v[178:181], v[156:159], v[20:23]
	ds_read2_b64 v[156:159], v182 offset0:8 offset1:12
	v_mfma_f32_16x16x32_bf16 v[56:59], v[178:181], v[164:167], v[56:59]
	s_waitcnt lgkmcnt(0)
	v_mfma_f32_16x16x32_bf16 v[20:23], v[156:159], v[152:155], v[20:23]
	v_mfma_f32_16x16x32_bf16 v[56:59], v[156:159], v[160:163], v[56:59]
	s_setprio 0

.LBB0_1016:
	s_add_i32 s6, s4, -1
	s_min_u32 s6, s6, s3
	s_mov_b32 s9, s7
	s_lshl_b32 s8, s6, 7
	v_lshl_add_u64 v[148:149], v[174:175], 0, s[8:9]
	s_mul_i32 s8, s6, 0x30000
	v_lshl_add_u64 v[144:145], v[172:173], 0, s[8:9]
	global_load_dwordx4 v[120:123], v[144:145], off offset:1024
	global_load_dwordx4 v[124:127], v[148:149], off
	ds_read_b128 v[152:155], v237
	ds_read_b128 v[156:159], v237 offset:64
	s_mov_b32 s6, 0xc000
	v_add_co_u32_e32 v128, vcc, s6, v144
	s_mov_b32 s6, 0xffff0000
	s_waitcnt lgkmcnt(1)
	v_mfma_f32_16x16x32_bf16 v[152:155], v[152:155], v[60:63], v[108:111]
	ds_read_b128 v[160:163], v237 offset:4416
	v_addc_co_u32_e32 v129, vcc, 0, v145, vcc
	s_waitcnt lgkmcnt(1)
	v_mfma_f32_16x16x32_bf16 v[152:155], v[156:159], v[64:67], v[152:155]
	ds_read_b128 v[156:159], v237 offset:4352
	v_add_co_u32_e32 v132, vcc, s10, v148
	global_load_dwordx4 v[128:131], v[128:129], off offset:1024
	s_nop 0
	v_addc_co_u32_e32 v133, vcc, 0, v149, vcc
	s_waitcnt lgkmcnt(0)
	v_mfma_f32_16x16x32_bf16 v[156:159], v[156:159], v[60:63], v[108:111]
	ds_read_b128 v[164:167], v237 offset:8768
	v_exp_f32_e32 v199, v155
	v_exp_f32_e32 v191, v153
	v_mfma_f32_16x16x32_bf16 v[156:159], v[160:163], v[64:67], v[156:159]
	ds_read_b128 v[160:163], v237 offset:8704
	v_add_co_u32_e32 v136, vcc, s11, v144
	s_waitcnt lgkmcnt(0)
	v_mfma_f32_16x16x32_bf16 v[160:163], v[160:163], v[60:63], v[108:111]
	s_nop 2
	s_nop 0
	v_exp_f32_e32 v197, v157
	v_exp_f32_e32 v189, v156
	v_mfma_f32_16x16x32_bf16 v[180:183], v[164:167], v[64:67], v[160:163]
	ds_read_b128 v[164:167], v237 offset:13120
	v_exp_f32_e32 v195, v158
	v_exp_f32_e32 v201, v159
	ds_read_b128 v[160:163], v237 offset:13056
	s_waitcnt lgkmcnt(0)
	v_mfma_f32_16x16x32_bf16 v[160:163], v[160:163], v[60:63], v[108:111]
	s_nop 1
	v_exp_f32_e32 v185, v183
	ds_read_b128 v[240:243], v237 offset:192
	v_exp_f32_e32 v181, v181
	v_mfma_f32_16x16x32_bf16 v[220:223], v[164:167], v[64:67], v[160:163]
	v_exp_f32_e32 v167, v154
	v_exp_f32_e32 v165, v152
	s_nop 0
	v_exp_f32_e32 v161, v180
	s_nop 2
	s_nop 0
	v_exp_f32_e32 v179, v220
	v_exp_f32_e32 v187, v221
	v_exp_f32_e32 v183, v222
	v_exp_f32_e32 v193, v223
	ds_read_b128 v[220:223], v237 offset:128
	s_waitcnt lgkmcnt(0)
	v_mfma_f32_16x16x32_bf16 v[220:223], v[220:223], v[68:71], v[108:111]
	ds_read_b128 v[244:247], v237 offset:4544
	ds_read_b128 v[224:227], v237 offset:8896
	v_mfma_f32_16x16x32_bf16 v[220:223], v[240:243], v[72:75], v[220:223]
	ds_read_b128 v[240:243], v237 offset:4480
	v_exp_f32_e32 v163, v182
	s_waitcnt lgkmcnt(0)
	v_mfma_f32_16x16x32_bf16 v[240:243], v[240:243], v[68:71], v[108:111]
	v_mfma_f32_16x16x32_bf16 v[240:243], v[244:247], v[72:75], v[240:243]
	ds_read_b128 v[244:247], v237 offset:8832
	v_cvt_pk_bf16_f32 v157, v167, v199
	s_waitcnt lgkmcnt(0)
	v_mfma_f32_16x16x32_bf16 v[244:247], v[244:247], v[68:71], v[108:111]
	v_mfma_f32_16x16x32_bf16 v[224:227], v[224:227], v[72:75], v[244:247]
	ds_read_b128 v[210:213], v237 offset:13248
	v_cvt_pk_bf16_f32 v156, v165, v191
	s_nop 0
	s_nop 3
	ds_read_b128 v[244:247], v237 offset:13184
	v_exp_f32_e32 v164, v220
	v_exp_f32_e32 v190, v221
	v_exp_f32_e32 v166, v222
	s_waitcnt lgkmcnt(0)
	v_mfma_f32_16x16x32_bf16 v[244:247], v[244:247], v[68:71], v[108:111]
	v_exp_f32_e32 v198, v223
	v_exp_f32_e32 v188, v240
	v_pk_add_f32 v[220:221], v[164:165], 0 op_sel_hi:[1,0]
	v_exp_f32_e32 v196, v241
	v_pk_add_f32 v[220:221], v[190:191], v[220:221]
	v_cvt_pk_bf16_f32 v159, v195, v201
	v_exp_f32_e32 v194, v242
	v_pk_add_f32 v[220:221], v[166:167], v[220:221]
	v_cvt_pk_bf16_f32 v158, v189, v197
	v_mfma_f32_16x16x32_bf16 v[210:213], v[210:213], v[72:75], v[244:247]
	v_add_f32_e64 v220, v198, v220
	v_add_f32_e64 v221, v199, v221
	v_exp_f32_e32 v200, v243
	v_cvt_pk_bf16_f32 v155, v183, v193
	v_cvt_pk_bf16_f32 v152, v161, v181
	v_pk_add_f32 v[220:221], v[220:221], v[188:189]
	v_exp_f32_e32 v160, v224
	v_cvt_pk_bf16_f32 v154, v179, v187
	v_cvt_pk_bf16_f32 v153, v163, v185
	v_pk_add_f32 v[220:221], v[196:197], v[220:221]
	v_exp_f32_e32 v180, v225
	v_pk_add_f32 v[220:221], v[194:195], v[220:221]
	v_exp_f32_e32 v162, v226
	v_exp_f32_e32 v184, v227
	v_exp_f32_e32 v178, v210
	v_exp_f32_e32 v186, v211
	v_pk_add_f32 v[210:211], v[200:201], v[220:221]
	v_exp_f32_e32 v182, v212
	v_pk_add_f32 v[210:211], v[210:211], v[160:161]
	v_pk_add_f32 v[210:211], v[180:181], v[210:211]
	v_pk_add_f32 v[210:211], v[162:163], v[210:211]
	v_bfe_u32 v165, v166, 16, 1
	v_pk_add_f32 v[210:211], v[184:185], v[210:211]
	v_pk_add_f32 v[210:211], v[210:211], v[178:179]
	v_exp_f32_e32 v192, v213
	v_pk_add_f32 v[210:211], v[186:187], v[210:211]
	v_bfe_u32 v163, v198, 16, 1
	v_add3_u32 v165, v166, v165, s33
	v_pk_add_f32 v[210:211], v[182:183], v[210:211]
	v_add3_u32 v163, v198, v163, s33
	v_lshrrev_b32_e32 v165, 16, v165
	v_and_or_b32 v165, v163, s6, v165
	v_cvt_pk_bf16_f32 v166, v188, v196
	v_bfe_u32 v163, v184, 16, 1
	v_add3_u32 v183, v184, v163, s33
	v_bfe_u32 v163, v162, 16, 1
	v_bfe_u32 v181, v182, 16, 1
	v_bfe_u32 v185, v178, 16, 1
	v_cvt_pk_bf16_f32 v167, v194, v200
	v_cvt_pk_bf16_f32 v164, v164, v190
	v_bfe_u32 v161, v192, 16, 1
	v_bfe_u32 v179, v186, 16, 1
	v_add3_u32 v181, v182, v181, s33
	v_add3_u32 v162, v162, v163, s33
	v_add3_u32 v163, v178, v185, s33
	v_add3_u32 v161, v192, v161, s33
	v_add3_u32 v179, v186, v179, s33
	v_lshrrev_b32_e32 v162, 16, v162
	v_lshrrev_b32_e32 v178, 16, v181
	v_lshrrev_b32_e32 v181, 16, v163
	v_add_u32_e32 v182, 0x4000, v238
	v_and_or_b32 v163, v161, s6, v178
	v_and_or_b32 v161, v183, s6, v162
	v_and_or_b32 v162, v179, s6, v181
	v_cvt_pk_bf16_f32 v160, v160, v180
	s_setprio 1
	ds_read2_b64 v[178:181], v182 offset0:128 offset1:132
	ds_read2_b64 v[216:219], v182 offset0:136 offset1:140
	s_waitcnt lgkmcnt(1)
; DEVI void attn_prompt_item(const Params& p, int l, int bq, int h, int qc, char* smem) {
;     ...
;   __syncthreads();
;   AT_LOAD(RK0, RV0, 0);
;   AT_LOAD(RK1, RV1, 1);
;   AT_STORE(RK0, RV0, 0);
;   AT_LOAD(RK0, RV0, 2);
;   AT_STORE(RK1, RV1, 1);
;   lds_barrier();
;   for (int kt = 0; kt < nkt; kt += 2) {
;     AT_LOAD(RK1, RV1, kt + 3);
;     AT_COMPUTE(0);
;     lds_barrier();
;     AT_STORE(RK0, RV0, 0);
;     if (kt + 1 < nkt) {
;       AT_LOAD(RK0, RV0, kt + 4);
;       AT_COMPUTE(1);
;     }
;     lds_barrier();
;     AT_STORE(RK1, RV1, 1);
;   }
	v_mfma_f32_16x16x32_bf16 v[76:79], v[178:181], v[156:159], v[76:79]
	v_addc_co_u32_e32 v137, vcc, 0, v145, vcc
	v_add_co_u32_e32 v140, vcc, s12, v148
	v_mfma_f32_16x16x32_bf16 v[80:83], v[178:181], v[164:167], v[80:83]
	v_add_u32_e32 v182, 0x4800, v238
	v_addc_co_u32_e32 v141, vcc, 0, v149, vcc
	ds_read2_b64 v[178:181], v182 offset0:160 offset1:164
	s_waitcnt lgkmcnt(1)
	v_mfma_f32_16x16x32_bf16 v[76:79], v[216:219], v[152:155], v[76:79]
	v_add_co_u32_e32 v144, vcc, s13, v144
	global_load_dwordx4 v[132:135], v[132:133], off
	v_mfma_f32_16x16x32_bf16 v[80:83], v[216:219], v[160:163], v[80:83]
	v_addc_co_u32_e32 v145, vcc, 0, v145, vcc
	ds_read2_b64 v[216:219], v182 offset0:168 offset1:172
	s_waitcnt lgkmcnt(1)
	v_mfma_f32_16x16x32_bf16 v[24:27], v[178:181], v[156:159], v[24:27]
	v_add_co_u32_e32 v148, vcc, s14, v148
	global_load_dwordx4 v[136:139], v[136:137], off offset:1024
	v_mfma_f32_16x16x32_bf16 v[36:39], v[178:181], v[164:167], v[36:39]
	v_add_u32_e32 v182, 0x5000, v238
	v_addc_co_u32_e32 v149, vcc, 0, v149, vcc
	ds_read2_b64 v[178:181], v182 offset0:192 offset1:196
	s_waitcnt lgkmcnt(1)
	v_mfma_f32_16x16x32_bf16 v[24:27], v[216:219], v[152:155], v[24:27]
	global_load_dwordx4 v[140:143], v[140:141], off
	s_add_i32 s5, s4, -4
	global_load_dwordx4 v[144:147], v[144:145], off offset:1024
	v_mfma_f32_16x16x32_bf16 v[36:39], v[216:219], v[160:163], v[36:39]
	global_load_dwordx4 v[148:151], v[148:149], off
	v_pk_add_f32 v[210:211], v[192:193], v[210:211]
	ds_read2_b64 v[216:219], v182 offset0:200 offset1:204
	s_waitcnt lgkmcnt(1)
	v_mfma_f32_16x16x32_bf16 v[16:19], v[178:181], v[156:159], v[16:19]
	v_add_f32_e64 v176, v176, v210
	v_add_f32_e64 v177, v177, v211
	s_cmp_ge_u32 s5, s3
	v_mfma_f32_16x16x32_bf16 v[32:35], v[178:181], v[164:167], v[32:35]
	v_add_u32_e32 v182, 0x5800, v238
	ds_read2_b64 v[178:181], v182 offset0:224 offset1:228
	s_waitcnt lgkmcnt(1)
	v_mfma_f32_16x16x32_bf16 v[16:19], v[216:219], v[152:155], v[16:19]
	v_mfma_f32_16x16x32_bf16 v[32:35], v[216:219], v[160:163], v[32:35]
	ds_read2_b64 v[216:219], v182 offset0:232 offset1:236
	s_waitcnt lgkmcnt(1)
	v_mfma_f32_16x16x32_bf16 v[28:31], v[178:181], v[156:159], v[28:31]
	v_mfma_f32_16x16x32_bf16 v[44:47], v[178:181], v[164:167], v[44:47]
	v_add_u32_e32 v182, 0x6800, v238
	ds_read2_b64 v[178:181], v182 offset1:4
	s_waitcnt lgkmcnt(1)
	v_mfma_f32_16x16x32_bf16 v[28:31], v[216:219], v[152:155], v[28:31]
	v_mfma_f32_16x16x32_bf16 v[44:47], v[216:219], v[160:163], v[44:47]
	ds_read2_b64 v[216:219], v182 offset0:8 offset1:12
	s_waitcnt lgkmcnt(1)
	v_mfma_f32_16x16x32_bf16 v[40:43], v[178:181], v[156:159], v[40:43]
	v_mfma_f32_16x16x32_bf16 v[52:55], v[178:181], v[164:167], v[52:55]
	v_add_u32_e32 v182, 0x7000, v238
	ds_read2_b64 v[178:181], v182 offset0:32 offset1:36
	s_waitcnt lgkmcnt(1)
	v_mfma_f32_16x16x32_bf16 v[40:43], v[216:219], v[152:155], v[40:43]
	v_mfma_f32_16x16x32_bf16 v[52:55], v[216:219], v[160:163], v[52:55]
	ds_read2_b64 v[216:219], v182 offset0:40 offset1:44
	s_waitcnt lgkmcnt(1)
	v_mfma_f32_16x16x32_bf16 v[12:15], v[178:181], v[156:159], v[12:15]
	v_mfma_f32_16x16x32_bf16 v[48:51], v[178:181], v[164:167], v[48:51]
	v_add_u32_e32 v182, 0x7800, v238
	ds_read2_b64 v[178:181], v182 offset0:64 offset1:68
	s_waitcnt lgkmcnt(1)
	v_mfma_f32_16x16x32_bf16 v[12:15], v[216:219], v[152:155], v[12:15]
	v_mfma_f32_16x16x32_bf16 v[48:51], v[216:219], v[160:163], v[48:51]
	ds_read2_b64 v[216:219], v182 offset0:72 offset1:76
	s_waitcnt lgkmcnt(1)
	v_mfma_f32_16x16x32_bf16 v[4:7], v[178:181], v[156:159], v[4:7]
	v_mfma_f32_16x16x32_bf16 v[8:11], v[178:181], v[164:167], v[8:11]
	v_add_u32_e32 v182, 0x8000, v238
	ds_read2_b64 v[178:181], v182 offset0:96 offset1:100
	s_waitcnt lgkmcnt(1)
	v_mfma_f32_16x16x32_bf16 v[4:7], v[216:219], v[152:155], v[4:7]
	v_mfma_f32_16x16x32_bf16 v[8:11], v[216:219], v[160:163], v[8:11]
	s_waitcnt lgkmcnt(0)
	v_mfma_f32_16x16x32_bf16 v[20:23], v[178:181], v[156:159], v[20:23]
	s_setprio 0
	ds_read2_b64 v[156:159], v182 offset0:104 offset1:108
	s_waitcnt lgkmcnt(0)
	s_barrier
	v_mfma_f32_16x16x32_bf16 v[56:59], v[178:181], v[164:167], v[56:59]
	s_waitcnt vmcnt(15)
	ds_write_b128 v232, v[84:87]
	s_waitcnt vmcnt(14)
	ds_write_b128 v233, v[88:91] offset:17408
	s_waitcnt vmcnt(13)
	ds_write_b128 v232, v[92:95] offset:4352
	s_waitcnt vmcnt(12)
	ds_write_b128 v233, v[96:99] offset:22016
	s_waitcnt vmcnt(11)
	ds_write_b128 v232, v[100:103] offset:8704
	s_waitcnt vmcnt(10)
	ds_write_b128 v233, v[104:107] offset:26624
	s_waitcnt vmcnt(9)
	ds_write_b128 v232, v[112:115] offset:13056
	s_waitcnt vmcnt(8)
	ds_write_b128 v233, v[116:119] offset:31232
	s_waitcnt lgkmcnt(8)
	v_mfma_f32_16x16x32_bf16 v[20:23], v[156:159], v[152:155], v[20:23]
	v_mfma_f32_16x16x32_bf16 v[56:59], v[156:159], v[160:163], v[56:59]
	s_cbranch_scc0 .LBB0_1014
	s_mov_b32 s7, s9
	s_branch .LBB0_1015
